# bundle11 + P1/P10 tile order 4 M-tiles x 8 N-tiles per XCD round (was 8x4)
# speedup vs baseline: 1.0018x; 1.0018x over previous
.LBB0_283:
	s_cmp_lt_i32 s24, 2
	s_cselect_b64 s[0:1], -1, 0
	s_cmp_gt_i32 s25, 1
	s_cselect_b64 s[2:3], -1, 0
	s_and_b64 s[0:1], s[0:1], s[2:3]
	s_andn2_b64 vcc, exec, s[0:1]
	s_cbranch_vccnz .LBB0_354
	s_abs_i32 s0, s33
	v_cvt_f32_u32_e32 v1, s0
	s_sub_i32 s3, 0, s0
	s_abs_i32 s2, s20
	s_ashr_i32 s1, s20, 31
	v_rcp_iflag_f32_e32 v1, v1
	s_waitcnt lgkmcnt(0)
	s_barrier
	v_mul_f32_e32 v1, 0x4f7ffffe, v1
	v_cvt_u32_f32_e32 v1, v1
	s_nop 0
	v_readfirstlane_b32 s4, v1
	s_mul_i32 s3, s3, s4
	s_mul_hi_u32 s3, s4, s3
	s_add_i32 s4, s4, s3
	s_mul_hi_u32 s3, s2, s4
	s_mul_i32 s3, s3, s0
	s_sub_i32 s2, s2, s3
	s_sub_i32 s3, s2, s0
	s_cmp_ge_u32 s2, s0
	s_cselect_b32 s2, s3, s2
	s_sub_i32 s3, s2, s0
	s_cmp_ge_u32 s2, s0
	s_cselect_b32 s0, s3, s2
	s_xor_b32 s0, s0, s1
	s_sub_i32 s18, s0, s1
	s_cmpk_gt_i32 s18, 0x15ff
	v_readfirstlane_b32 s3, v0
	s_cbranch_scc1 .LBB0_300
	v_lshrrev_b32_e32 v1, 5, v0
	v_lshrrev_b32_e32 v3, 1, v0
	v_and_b32_e32 v1, 4, v1
	v_bfe_u32 v2, v0, 2, 2
	v_and_b32_e32 v13, 24, v3
	s_add_u32 s19, s26, 0x8000000
	v_or3_b32 v1, v1, v2, v13
	v_lshlrev_b32_e32 v2, 4, v0
	s_addc_u32 s22, s27, 0
	v_or_b32_e32 v10, 0x2000, v2
	s_add_u32 s23, s26, 0x100000
	v_lshrrev_b32_e32 v3, 7, v10
	s_movk_i32 s0, 0x60
	s_addc_u32 s28, s27, 0
	v_and_or_b32 v4, v3, s0, v1
	v_bfe_u32 v14, v0, 2, 4
	s_movk_i32 s0, 0x70
	s_ashr_i32 s31, s18, 31
	v_and_or_b32 v3, v3, s0, v14
	s_lshr_b32 s0, s31, 29
	s_add_i32 s0, s18, s0
	s_lshr_b32 s6, s3, 6
	s_ashr_i32 s1, s0, 3
	s_and_b32 s0, s0, -8
	s_lshr_b32 s8, s3, 8
	s_lshl_b32 s29, s6, 10
	s_sub_i32 s0, s18, s0
	s_cmp_lt_i32 s0, 0
	s_movk_i32 s56, 0x2c1
	s_cselect_b32 s2, s56, 0x2c0
	s_mul_i32 s0, s0, s2
	s_add_i32 s0, s0, s1
	s_mul_hi_i32 s1, s0, 0x2e8ba2e9
	s_lshr_b32 s1, s1, 5
	s_lshl_b32 s4, s1, 2
	s_mulk_i32 s1, 0xb0
	s_sub_i32 s0, s0, s1
	v_and_b32_e32 v5, 32, v0
	s_lshr_b32 s2, s0, 2
	s_and_b32 s0, s0, 3
	s_add_i32 s34, s4, s0
	v_bitop3_b32 v11, v2, v5, 48 bitop3:0x6c
	v_and_b32_e32 v12, 64, v0
	s_ashr_i32 s35, s34, 31
	s_bfe_i64 s[4:5], s[2:3], 0x100000
	v_or_b32_e32 v2, v11, v12
	s_lshl_b64 s[0:1], s[34:35], 20
	s_lshl_b64 s[4:5], s[4:5], 20
	v_lshl_or_b32 v132, v3, 12, v2
	v_lshrrev_b32_e32 v3, 3, v0
	s_add_u32 s42, s23, s4
	v_and_or_b32 v1, v3, 32, v1
	s_addc_u32 s43, s28, s5
	s_add_i32 s35, s29, 0
	v_lshl_or_b32 v134, v1, 12, v2
	s_add_i32 m0, s35, 0x10000
	v_lshl_or_b32 v130, v4, 12, v2
	global_load_lds_dwordx4 v134, s[42:43]
	s_add_i32 m0, s35, 0x12000
	s_add_u32 s4, s42, 0x80000
	global_load_lds_dwordx4 v130, s[42:43]
	s_addc_u32 s5, s43, 0
	s_add_i32 m0, s35, 0x14000
	v_and_or_b32 v1, v3, 48, v14
	global_load_lds_dwordx4 v134, s[4:5]
	s_add_i32 m0, s35, 0x16000
	s_add_u32 s40, s19, s0
	s_addc_u32 s41, s22, s1
	s_add_i32 s57, s35, 0x2000
	v_lshl_or_b32 v136, v1, 12, v2
	global_load_lds_dwordx4 v130, s[4:5]
	s_mov_b32 m0, s35
	s_add_u32 s0, s40, 0x80000
	global_load_lds_dwordx4 v136, s[40:41]
	s_mov_b32 m0, s57
	s_addc_u32 s1, s41, 0
	s_add_i32 s58, s35, 0x4000
	global_load_lds_dwordx4 v132, s[40:41]
	s_mov_b32 m0, s58
	s_add_i32 s59, s35, 0x6000
	global_load_lds_dwordx4 v136, s[0:1]
	s_mov_b32 m0, s59
	v_mov_b32_e32 v135, 0
	global_load_lds_dwordx4 v132, s[0:1]
	v_mov_b32_e32 v131, v135
	v_mov_b32_e32 v137, v135
	v_mov_b32_e32 v133, v135
	s_cmp_eq_u32 s8, 1
	v_lshl_add_u64 v[8:9], s[42:43], 0, v[134:135]
	v_lshl_add_u64 v[6:7], s[42:43], 0, v[130:131]
	v_lshl_add_u64 v[2:3], s[40:41], 0, v[136:137]
	s_cselect_b64 s[0:1], -1, 0
	s_cmp_lg_u32 s8, 1
	v_lshl_add_u64 v[4:5], s[40:41], 0, v[132:133]
	s_cbranch_scc1 .LBB0_287
	s_barrier

.LBB0_290:
	s_add_i32 s66, s66, 1
	s_mul_i32 s2, s66, s67
	s_mul_hi_u32 s3, s66, s33
	s_add_i32 s3, s3, s2
	s_mul_i32 s2, s66, s33
	s_add_u32 s14, s2, s18
	s_addc_u32 s15, s3, s31
	v_cmp_gt_i64_e32 vcc, s[14:15], v[144:145]
	v_cmp_lt_i64_e64 s[2:3], s[14:15], v[142:143]
	s_cbranch_vccnz .LBB0_292
	s_ashr_i32 s10, s14, 31
	s_lshr_b32 s10, s10, 29
	s_add_i32 s10, s14, s10
	s_ashr_i32 s11, s10, 3
	s_and_b32 s10, s10, -8
	s_sub_i32 s10, s14, s10
	s_cmp_lt_i32 s10, 0
	s_cselect_b32 s12, s56, 0x2c0
	s_mul_i32 s10, s10, s12
	s_add_i32 s10, s10, s11
	s_mul_hi_i32 s11, s10, 0x2e8ba2e9
	s_lshr_b32 s11, s11, 5
	s_lshl_b32 s12, s11, 2
	s_mulk_i32 s11, 0xb0
	s_sub_i32 s11, s10, s11
	s_lshr_b32 s10, s11, 2
	s_and_b32 s11, s11, 3
	s_add_i32 s12, s12, s11

.LBB0_1469:
	s_cmp_lt_i32 s24, 11
	s_cselect_b64 s[0:1], -1, 0
	s_cmp_gt_i32 s25, 10
	s_cselect_b64 s[2:3], -1, 0
	s_and_b64 s[0:1], s[0:1], s[2:3]
	s_andn2_b64 vcc, exec, s[0:1]
	s_cbranch_vccnz .LBB0_1544
	s_abs_i32 s0, s33
	v_cvt_f32_u32_e32 v1, s0
	s_sub_i32 s3, 0, s0
	s_abs_i32 s2, s20
	s_ashr_i32 s1, s20, 31
	v_rcp_iflag_f32_e32 v1, v1
	s_waitcnt vmcnt(0) lgkmcnt(0)
	s_barrier
	v_mul_f32_e32 v1, 0x4f7ffffe, v1
	v_cvt_u32_f32_e32 v1, v1
	s_nop 0
	v_readfirstlane_b32 s4, v1
	s_mul_i32 s3, s3, s4
	s_mul_hi_u32 s3, s4, s3
	s_add_i32 s4, s4, s3
	s_mul_hi_u32 s3, s2, s4
	s_mul_i32 s3, s3, s0
	s_sub_i32 s2, s2, s3
	s_sub_i32 s3, s2, s0
	s_cmp_ge_u32 s2, s0
	s_cselect_b32 s2, s3, s2
	s_sub_i32 s3, s2, s0
	s_cmp_ge_u32 s2, s0
	s_cselect_b32 s0, s3, s2
	s_xor_b32 s0, s0, s1
	s_sub_i32 s18, s0, s1
	s_cmpk_gt_i32 s18, 0x15ff
	v_readfirstlane_b32 s3, v0
	s_cbranch_scc1 .LBB0_1490
	v_lshrrev_b32_e32 v1, 5, v0
	v_lshrrev_b32_e32 v3, 1, v0
	v_and_b32_e32 v1, 4, v1
	v_bfe_u32 v2, v0, 2, 2
	v_and_b32_e32 v13, 24, v3
	s_add_u32 s19, s26, 0x27c00000
	v_or3_b32 v1, v1, v2, v13
	v_lshlrev_b32_e32 v2, 4, v0
	s_addc_u32 s22, s27, 0
	v_or_b32_e32 v10, 0x2000, v2
	s_add_u32 s23, s26, 0x100000
	v_lshrrev_b32_e32 v3, 7, v10
	s_movk_i32 s0, 0x60
	s_addc_u32 s28, s27, 0
	v_and_or_b32 v4, v3, s0, v1
	v_bfe_u32 v14, v0, 2, 4
	s_movk_i32 s0, 0x70
	s_ashr_i32 s42, s18, 31
	v_and_or_b32 v3, v3, s0, v14
	s_lshr_b32 s0, s42, 29
	s_add_i32 s0, s18, s0
	s_lshr_b32 s7, s3, 6
	s_ashr_i32 s1, s0, 3
	s_and_b32 s0, s0, -8
	s_lshr_b32 s6, s3, 8
	s_lshl_b32 s29, s7, 10
	s_sub_i32 s0, s18, s0
	s_cmp_lt_i32 s0, 0
	s_movk_i32 s43, 0x2c1
	s_cselect_b32 s2, s43, 0x2c0
	s_mul_i32 s0, s0, s2
	s_add_i32 s0, s0, s1
	s_mul_hi_i32 s1, s0, 0x2e8ba2e9
	s_lshr_b32 s1, s1, 5
	s_lshl_b32 s4, s1, 2
	s_mulk_i32 s1, 0xb0
	s_sub_i32 s0, s0, s1
	v_and_b32_e32 v5, 32, v0
	s_lshr_b32 s2, s0, 2
	s_and_b32 s0, s0, 3
	s_add_i32 s10, s4, s0
	v_bitop3_b32 v11, v2, v5, 48 bitop3:0x6c
	v_and_b32_e32 v12, 64, v0
	s_ashr_i32 s11, s10, 31
	s_bfe_i64 s[4:5], s[2:3], 0x100000
	v_or_b32_e32 v2, v11, v12
	s_lshl_b64 s[0:1], s[10:11], 20
	s_lshl_b64 s[4:5], s[4:5], 20
	v_lshl_or_b32 v140, v3, 12, v2
	v_lshrrev_b32_e32 v3, 3, v0
	s_add_u32 s4, s23, s4
	v_and_or_b32 v1, v3, 32, v1
	s_addc_u32 s5, s28, s5
	s_add_i32 s44, s29, 0
	v_lshl_or_b32 v142, v1, 12, v2
	s_add_i32 m0, s44, 0x10000
	v_lshl_or_b32 v138, v4, 12, v2
	global_load_lds_dwordx4 v142, s[4:5]
	s_add_i32 m0, s44, 0x12000
	s_add_u32 s8, s4, 0x80000
	global_load_lds_dwordx4 v138, s[4:5]
	s_addc_u32 s9, s5, 0
	s_add_i32 m0, s44, 0x14000
	v_and_or_b32 v1, v3, 48, v14
	global_load_lds_dwordx4 v142, s[8:9]
	s_add_i32 m0, s44, 0x16000
	s_add_u32 s0, s19, s0
	s_addc_u32 s1, s22, s1
	s_add_i32 s45, s44, 0x2000
	v_lshl_or_b32 v144, v1, 12, v2
	global_load_lds_dwordx4 v138, s[8:9]
	s_mov_b32 m0, s44
	s_add_u32 s8, s0, 0x80000
	global_load_lds_dwordx4 v144, s[0:1]
	s_mov_b32 m0, s45
	s_addc_u32 s9, s1, 0
	s_add_i32 s46, s44, 0x4000
	global_load_lds_dwordx4 v140, s[0:1]
	s_mov_b32 m0, s46
	s_add_i32 s47, s44, 0x6000
	global_load_lds_dwordx4 v144, s[8:9]
	s_mov_b32 m0, s47
	v_mov_b32_e32 v143, 0
	global_load_lds_dwordx4 v140, s[8:9]
	v_mov_b32_e32 v139, v143
	v_mov_b32_e32 v145, v143
	v_mov_b32_e32 v141, v143
	s_cmp_eq_u32 s6, 1
	v_lshl_add_u64 v[8:9], s[4:5], 0, v[142:143]
	v_lshl_add_u64 v[6:7], s[4:5], 0, v[138:139]
	v_lshl_add_u64 v[2:3], s[0:1], 0, v[144:145]
	s_cselect_b64 s[12:13], -1, 0
	s_cmp_lg_u32 s6, 1
	v_lshl_add_u64 v[4:5], s[0:1], 0, v[140:141]
	s_cbranch_scc1 .LBB0_1473
	s_barrier

.LBB0_1476:
	s_add_i32 s52, s52, 1
	s_mul_i32 s2, s52, s53
	s_mul_hi_u32 s3, s52, s33
	s_add_i32 s3, s3, s2
	s_mul_i32 s2, s52, s33
	s_add_u32 s6, s2, s18
	s_addc_u32 s7, s3, s42
	v_cmp_gt_i64_e32 vcc, s[6:7], v[152:153]
	s_mov_b32 s58, s10
	v_cmp_lt_i64_e64 s[2:3], s[6:7], v[150:151]
	s_cbranch_vccnz .LBB0_1478
	s_ashr_i32 s7, s6, 31
	s_lshr_b32 s7, s7, 29
	s_add_i32 s7, s6, s7
	s_ashr_i32 s9, s7, 3
	s_and_b32 s7, s7, -8
	s_sub_i32 s6, s6, s7
	s_cmp_lt_i32 s6, 0
	s_cselect_b32 s7, s43, 0x2c0
	s_mul_i32 s6, s6, s7
	s_add_i32 s6, s6, s9
	s_mul_hi_i32 s7, s6, 0x2e8ba2e9
	s_lshr_b32 s7, s7, 5
	s_lshl_b32 s9, s7, 2
	s_mulk_i32 s7, 0xb0
	s_sub_i32 s6, s6, s7
	s_lshr_b32 s36, s6, 2
	s_and_b32 s6, s6, 3
	s_add_i32 s10, s9, s6
